# v17 with the grid-stride outer loop restored around the 4-head loop (valid for any grid size)
# baseline (speedup 1.0000x reference)
; __device__ __forceinline__ unsigned pk2(float lo, float hi) { f32x2 v = {lo, hi}; bf16x2_t b = __builtin_convertvector(v, bf16x2_t); return __builtin_bit_cast(unsigned, b); }
; __device__ __forceinline__ float bf_lo(unsigned w) { return __uint_as_float(w << 16); }
; __device__ __forceinline__ float bf_hi(unsigned w) { return __uint_as_float(w & 0xffff0000u); }
; __device__ __forceinline__ void attn_phase(LAS unsigned char* lds, unsigned char* ws, int l) {
;     ...
;     for (int vb = blockIdx.x; vb < 256; vb += gridDim.x) {
;         const int v2 = (vb & 7) * 32 + (vb >> 3);
;         const int j = v2 & 7, h = (v2 >> 3) & 7, b = v2 >> 6;
;     ...
;             for (int r = 0; r < 32; ++r) { const size_t t = (size_t)b * SEQ + qblk * 256 + wv * 32 + r;
;                 const u32x2 a = *(const u32x2*)(O12 + t * 4096 + h * 256 + 4 * lane), bb = *(const u32x2*)(O12 + t * 4096 + 2048 + h * 256 + 4 * lane);
;                 f32x4 o = (f32x4){bf_lo(a.x), bf_hi(a.x), bf_lo(a.y), bf_hi(a.y)} - (f32x4){bf_lo(bb.x), bf_hi(bb.x), bf_lo(bb.y), bf_hi(bb.y)} * lam;
;                 const float ss = wave_sum(o[0] * o[0] + o[1] * o[1] + o[2] * o[2] + o[3] * o[3]);
;                 const float rs = 1.0f / sqrtf(ss * (1.0f / 256.0f) + SUBLN_EPS);
;                 o = o * rs * g;
;                 u32x2 w; w.x = pk2(o[0], o[1]); w.y = pk2(o[2], o[3]);
;                 *(u32x2*)(OB + t * DM + h * 256 + 4 * lane) = w; }
.LBB0_285:
	v_add_co_u32_e32 v20, vcc, 0x1000, v6
	global_load_dwordx2 v[18:19], v[6:7], off
	s_nop 0
	v_addc_co_u32_e32 v21, vcc, 0, v7, vcc
	global_load_dwordx2 v[20:21], v[20:21], off
	v_xor_b32_e32 v27, 0x80000000, v3
	v_xor_b32_e32 v26, 0x80000000, v2
	s_waitcnt vmcnt(1)
	v_lshlrev_b32_e32 v22, 16, v18
	v_and_b32_e32 v23, 0xffff0000, v18
	v_lshlrev_b32_e32 v18, 16, v19
	v_and_b32_e32 v19, 0xffff0000, v19
	s_waitcnt vmcnt(0)
	v_lshlrev_b32_e32 v24, 16, v20
	v_and_b32_e32 v25, 0xffff0000, v20
	v_lshlrev_b32_e32 v20, 16, v21
	v_and_b32_e32 v21, 0xffff0000, v21
	v_pk_fma_f32 v[18:19], v[26:27], v[20:21], v[18:19]
	v_pk_fma_f32 v[20:21], v[12:13], v[24:25], v[22:23] neg_lo:[1,0,0] neg_hi:[1,0,0]
	v_pk_mul_f32 v[22:23], v[18:19], v[18:19]
	v_mul_f32_e32 v24, v21, v21
	v_fmac_f32_e32 v24, v20, v20
	v_add_f32_e32 v22, v22, v24
	v_add_f32_e32 v22, v23, v22
	ds_bpermute_b32 v23, v0, v22
	s_waitcnt lgkmcnt(0)
	v_add_f32_e32 v22, v22, v23
	ds_bpermute_b32 v23, v14, v22
	s_waitcnt lgkmcnt(0)
	v_add_f32_e32 v22, v22, v23
	ds_bpermute_b32 v23, v15, v22
	s_waitcnt lgkmcnt(0)
	v_add_f32_e32 v22, v22, v23
	ds_bpermute_b32 v23, v16, v22
	s_waitcnt lgkmcnt(0)
	v_add_f32_e32 v22, v22, v23
	ds_bpermute_b32 v23, v17, v22
	s_waitcnt lgkmcnt(0)
	v_add_f32_e32 v22, v22, v23
	ds_bpermute_b32 v23, v131, v22
	s_waitcnt lgkmcnt(0)
	v_add_f32_e32 v22, v22, v23
	v_fmamk_f32 v22, v22, 0x3b800000, v225
	v_cmp_gt_f32_e32 vcc, s91, v22
	v_mul_f32_e32 v23, 0x4f800000, v22
	s_nop 0
	v_cndmask_b32_e32 v22, v22, v23, vcc
	v_sqrt_f32_e32 v23, v22
	s_nop 0
	v_add_u32_e32 v24, -1, v23
	v_fma_f32 v25, -v24, v23, v22
	v_cmp_ge_f32_e64 s[0:1], 0, v25
	v_add_u32_e32 v25, 1, v23
	s_nop 0
	v_cndmask_b32_e64 v24, v23, v24, s[0:1]
	v_fma_f32 v23, -v25, v23, v22
	v_cmp_lt_f32_e64 s[0:1], 0, v23
	s_nop 1
	v_cndmask_b32_e64 v23, v24, v25, s[0:1]
	v_mul_f32_e32 v24, 0x37800000, v23
	v_cndmask_b32_e32 v23, v23, v24, vcc
	v_cmp_class_f32_e32 vcc, v22, v226
	s_nop 1
	v_cndmask_b32_e32 v22, v23, v22, vcc
	v_div_scale_f32 v23, s[0:1], v22, v22, 1.0
	v_rcp_f32_e32 v24, v23
	s_mov_b64 s[0:1], 0x2000
	v_lshl_add_u64 v[6:7], v[6:7], 0, s[0:1]
	v_fma_f32 v25, -v23, v24, 1.0
	v_fmac_f32_e32 v24, v25, v24
	v_div_scale_f32 v25, vcc, 1.0, v22, 1.0
	v_mul_f32_e32 v26, v25, v24
	v_fma_f32 v27, -v23, v26, v25
	v_fmac_f32_e32 v26, v27, v24
	v_fma_f32 v23, -v23, v26, v25
	v_div_fmas_f32 v23, v23, v24, v26
	v_div_fixup_f32 v22, v23, v22, 1.0
	v_pk_mul_f32 v[20:21], v[20:21], v[22:23] op_sel_hi:[1,0]
	v_pk_mul_f32 v[18:19], v[18:19], v[22:23] op_sel_hi:[1,0]
	v_pk_mul_f32 v[20:21], v[10:11], v[20:21]
	v_pk_mul_f32 v[18:19], v[8:9], v[18:19]
	v_cvt_pk_bf16_f32 v20, v20, v21
	v_cvt_pk_bf16_f32 v21, v18, v19
	v_lshl_add_u64 v[18:19], v[4:5], 0, s[36:37]
	s_add_u32 s36, s36, 0x1000
	s_addc_u32 s37, s37, 0
	s_cmp_eq_u32 s36, 0x10000
	global_store_dwordx2 v[18:19], v[20:21], off
	s_cbranch_scc0 .LBB0_285
	s_add_i32 s98, s98, 1
	s_cmp_lt_u32 s98, 4
	s_cbranch_scc1 .LBB0_249
	s_add_i32 s27, s27, s3
	s_mov_b32 s98, 0
	s_cmpk_gt_i32 s27, 0xff
	s_cbranch_scc0 .LBB0_249
	s_setprio 0
	v_readlane_b32 s48, v255, 6
	v_readlane_b32 s49, v255, 7
	v_readlane_b32 s93, v255, 12
	s_mov_b32 s40, s50
